# HGRN pass-2 loop: scalar address products + v_lshl_add_u64 instead of nine v_mad_u64_u32 per step
# baseline (speedup 1.0000x reference)
; template <bool FULL>
; __device__ __forceinline__ void hgrn_item(LAS unsigned char* lds, const bf16_t* P, bf16_t* AB, int L, int hd, const float* lbv, const float* anorm, const float* S0, const float* Dd, int ns, float* Sout, float* Dout) {
;     ...
;         const size_t roff = (size_t)(16 * n) * N1;
;         {
;             const size_t nro = (size_t)(16 * (n + 1 < nsteps ? n + 1 : n)) * N1;
; #pragma unroll
;             for (int i = 0; i < 4; ++i) { zr[i] = pz[nro + (size_t)i * N1]; qr[i] = pq[nro + (size_t)i * N1]; grn[i] = pg[nro + (size_t)i * N1]; }
;             if (tid < 256) vr = *(const u32x4*)(pv + nro);
.LBB0_331:
	s_mov_b32 s0, s2
	s_add_i32 s2, s2, 1
	s_cmp_lt_u32 s0, 31
	s_cselect_b32 s0, s2, s0
	s_lshl_b32 s3, s0, 4
	s_mul_i32 s8, s3, 0x2c00
	s_mov_b32 s9, 0
	v_lshl_add_u64 v[48:49], v[74:75], 0, s[8:9]
	global_load_ushort v101, v[48:49], off offset:1024
	global_load_ushort v105, v[48:49], off
	v_lshl_add_u64 v[48:49], v[76:77], 0, s[8:9]
	global_load_ushort v107, v[48:49], off offset:3072
	s_add_u32 s8, s8, 0x2c00
	v_lshl_add_u64 v[48:49], v[74:75], 0, s[8:9]
	global_load_ushort v106, v[48:49], off offset:1024
	global_load_ushort v108, v[48:49], off
	v_lshl_add_u64 v[48:49], v[76:77], 0, s[8:9]
	global_load_ushort v109, v[48:49], off offset:3072
	s_add_u32 s8, s8, 0x2c00
	v_lshl_add_u64 v[48:49], v[74:75], 0, s[8:9]
	global_load_ushort v110, v[48:49], off offset:1024
	global_load_ushort v111, v[48:49], off
	v_lshl_add_u64 v[48:49], v[76:77], 0, s[8:9]
	global_load_ushort v113, v[48:49], off offset:3072
	s_add_u32 s8, s8, 0x2c00
	v_lshl_add_u64 v[48:49], v[74:75], 0, s[8:9]
	global_load_ushort v112, v[48:49], off offset:1024
	global_load_ushort v114, v[48:49], off
	v_lshl_add_u64 v[48:49], v[76:77], 0, s[8:9]
	global_load_ushort v115, v[48:49], off offset:3072
	s_and_saveexec_b64 s[0:1], vcc
	s_cbranch_execz .LBB0_333
	s_mul_i32 s8, s3, 0x2c00
	v_lshl_add_u64 v[32:33], v[78:79], 0, s[8:9]
	global_load_dwordx4 v[32:35], v[32:33], off offset:2048
